# attention: waves 4-7 do K/V staging+prefetch at the end of each tile iteration (stagger vs SIMD partner waves 0-3)
# baseline (speedup 1.0000x reference)
; #define ATT_QPTR(UNIT) (qkv + (size_t)((((UNIT) & 127) >> 4) * 2048 + (2 * ATT_U(UNIT) + (w >> 2)) * 64 + (w & 3) * 16 + i16) * NPROJ + ((UNIT) & 15) * 128 + g * 8)
; #define ATT_KCLO(UNIT) ((2 * ATT_U(UNIT) - 8 > 0) ? (2 * ATT_U(UNIT) - 8) : 0)
; #define ATT_LOADP(KB, kc) do { const bf16* p_ = (KB) + (size_t)(kc) * 64 * NPROJ; rk0 = *(const v4u*)p_; rk1 = *(const v4u*)(p_ + (size_t)32 * NPROJ); \
;                           rv0 = *(const v4u*)(p_ + 2048); rv1 = *(const v4u*)(p_ + (size_t)32 * NPROJ + 2048); } while (0)
; #define ATT_LOAD(kc) do { const bf16* p_ = kbase + (size_t)(kc) * 64 * NPROJ; rk0 = *(const v4u*)p_; rk1 = *(const v4u*)(p_ + (size_t)32 * NPROJ); \
;                           rv0 = *(const v4u*)(p_ + 2048); rv1 = *(const v4u*)(p_ + (size_t)32 * NPROJ + 2048); } while (0)
; #define ATT_WRITE(buf) do { ATT_KNORM(rk0, srow, buf); ATT_KNORM(rk1, srow + 32, buf); \
;             *(LAS v4u*)(lds + VB0 + (buf) * VBUF + srow * VS + sch * 16) = rv0; *(LAS v4u*)(lds + VB0 + (buf) * VBUF + (srow + 32) * VS + sch * 16) = rv1; } while (0)
; __device__ __forceinline__ void attn_phase(LAS unsigned char* lds, const bf16* qkv, const float* gq, const float* gk, const float* relb, bf16* ao, int tid, int lane, int w) {
;     ...
;         for (int t = 0; t < ntiles; ++t) {
;             const int kc = kc_lo + t, buf = t & 1;
;             if (t + 1 < ntiles) ATT_WRITE(buf ^ 1);
;             if (t + 2 < ntiles) ATT_LOAD(kc + 2);
;             if (t == ntiles - 1 && nunit < 2048) { const bf16* qp_ = ATT_QPTR(nunit);
; #pragma unroll
;                 for (int ks = 0; ks < 4; ++ks) qr[ks] = __builtin_nontemporal_load((const v4u*)(qp_ + ks * 32));
;                 ATT_LOADP(ATT_KBASE(nunit), ATT_KCLO(nunit)); }
.LBB0_338:
	s_cmp_eq_u32 s24, 0
	s_cbranch_scc1 .Latt_late_done
	s_add_i32 s8, s22, -2
	s_and_b32 s8, s8, 1
	s_add_i32 s9, s22, -1
	s_cmp_ge_i32 s9, s5
	s_cbranch_scc1 .Latt_late_B
	s_waitcnt vmcnt(3)
	v_and_b32_e32 v89, 0xffff0000, v35
	v_and_b32_e32 v87, 0xffff0000, v34
	v_lshlrev_b32_e32 v88, 16, v35
	v_lshlrev_b32_e32 v86, 16, v34
	v_mov_b32_e32 v90, v89
	v_mov_b32_e32 v91, v87
	v_mov_b32_e32 v84, v88
	v_mov_b32_e32 v85, v86
	v_pk_mul_f32 v[90:91], v[90:91], v[90:91]
	v_and_b32_e32 v93, 0xffff0000, v32
	v_pk_fma_f32 v[84:85], v[84:85], v[84:85], v[90:91]
	v_and_b32_e32 v91, 0xffff0000, v33
	v_lshlrev_b32_e32 v90, 16, v33
	v_lshlrev_b32_e32 v92, 16, v32
	v_mov_b32_e32 v96, v93
	v_mov_b32_e32 v97, v91
	v_mov_b32_e32 v94, v92
	v_mov_b32_e32 v95, v90
	v_pk_mul_f32 v[96:97], v[96:97], v[96:97]
	s_xor_b32 s9, s8, 1
	v_pk_fma_f32 v[94:95], v[94:95], v[94:95], v[96:97]
	s_mul_i32 s10, s9, 0x4400
	v_add_f32_e32 v94, v94, v95
	v_add_f32_e32 v85, v85, v94
	v_add_f32_e32 v84, v84, v85
	s_add_i32 s10, s10, 0
	s_lshl_b32 s9, s9, 10
	v_add_f32_dpp v84, v84, v84 quad_perm:[1,0,3,2] row_mask:0xf bank_mask:0xf bound_ctrl:1
	s_nop 1
	v_add_f32_dpp v84, v84, v84 quad_perm:[2,3,0,1] row_mask:0xf bank_mask:0xf bound_ctrl:1
	s_nop 1
	v_add_f32_dpp v84, v84, v84 row_half_mirror row_mask:0xf bank_mask:0xf bound_ctrl:1
	s_nop 1
	v_add_f32_dpp v84, v84, v84 row_mirror row_mask:0xf bank_mask:0xf bound_ctrl:1
	v_fmamk_f32 v84, v84, 0x3c000000, v207
	v_rsq_f32_e32 v94, v84
	s_nop 0
	v_pk_mul_f32 v[84:85], v[94:95], v[92:93] op_sel_hi:[0,1]
	v_pk_mul_f32 v[90:91], v[94:95], v[90:91] op_sel_hi:[0,1]
	v_pk_mul_f32 v[86:87], v[94:95], v[86:87] op_sel_hi:[0,1]
	v_pk_mul_f32 v[88:89], v[94:95], v[88:89] op_sel_hi:[0,1]
	v_cvt_pk_bf16_f32 v84, v84, v85
	v_cvt_pk_bf16_f32 v85, v90, v91
	v_cvt_pk_bf16_f32 v86, v86, v87
	v_cvt_pk_bf16_f32 v87, v88, v89
	v_add3_u32 v88, s10, v103, v102
	ds_write_b128 v88, v[84:87]
	s_waitcnt vmcnt(2)
	v_and_b32_e32 v89, 0xffff0000, v23
	v_and_b32_e32 v87, 0xffff0000, v22
	v_lshlrev_b32_e32 v88, 16, v23
	v_lshlrev_b32_e32 v86, 16, v22
	v_mov_b32_e32 v90, v89
	v_mov_b32_e32 v91, v87
	v_mov_b32_e32 v84, v88
	v_mov_b32_e32 v85, v86
	v_pk_mul_f32 v[90:91], v[90:91], v[90:91]
	v_and_b32_e32 v93, 0xffff0000, v20
	v_pk_fma_f32 v[84:85], v[84:85], v[84:85], v[90:91]
	v_and_b32_e32 v91, 0xffff0000, v21
	v_lshlrev_b32_e32 v90, 16, v21
	v_lshlrev_b32_e32 v92, 16, v20
	v_mov_b32_e32 v96, v93
	v_mov_b32_e32 v97, v91
	v_mov_b32_e32 v94, v92
	v_mov_b32_e32 v95, v90
	v_pk_mul_f32 v[96:97], v[96:97], v[96:97]
	s_nop 0
	v_pk_fma_f32 v[94:95], v[94:95], v[94:95], v[96:97]
	s_nop 0
	v_add_f32_e32 v94, v94, v95
	v_add_f32_e32 v85, v85, v94
	v_add_f32_e32 v84, v84, v85
	s_nop 1
	v_add_f32_dpp v84, v84, v84 quad_perm:[1,0,3,2] row_mask:0xf bank_mask:0xf bound_ctrl:1
	s_nop 1
	v_add_f32_dpp v84, v84, v84 quad_perm:[2,3,0,1] row_mask:0xf bank_mask:0xf bound_ctrl:1
	s_nop 1
	v_add_f32_dpp v84, v84, v84 row_half_mirror row_mask:0xf bank_mask:0xf bound_ctrl:1
	s_nop 1
	v_add_f32_dpp v84, v84, v84 row_mirror row_mask:0xf bank_mask:0xf bound_ctrl:1
	v_fmamk_f32 v84, v84, 0x3c000000, v207
	v_rsq_f32_e32 v94, v84
	s_nop 0
	v_pk_mul_f32 v[84:85], v[94:95], v[92:93] op_sel_hi:[0,1]
	v_pk_mul_f32 v[90:91], v[94:95], v[90:91] op_sel_hi:[0,1]
	v_pk_mul_f32 v[86:87], v[94:95], v[86:87] op_sel_hi:[0,1]
	v_pk_mul_f32 v[88:89], v[94:95], v[88:89] op_sel_hi:[0,1]
	v_cvt_pk_bf16_f32 v84, v84, v85
	v_cvt_pk_bf16_f32 v85, v90, v91
	v_cvt_pk_bf16_f32 v86, v86, v87
	v_cvt_pk_bf16_f32 v87, v88, v89
	v_add3_u32 v88, s10, v170, v102
	s_add_i32 s10, s10, s9
	ds_write_b128 v88, v[84:87]
	v_add3_u32 v84, s10, v171, v102
	s_waitcnt vmcnt(1)
	ds_write_b128 v84, v[24:27] offset:34816
	v_add3_u32 v84, s10, v173, v102
	s_waitcnt vmcnt(0)
	ds_write_b128 v84, v[28:31] offset:34816
.Latt_late_B:
	s_cmp_ge_i32 s22, s5
	s_cbranch_scc1 .Latt_late_done
	s_add_i32 s9, s2, s22
	s_add_i32 s10, s9, -8
	s_waitcnt vmcnt(1)
	v_mad_i64_i32 v[24:25], s[10:11], s10, v211, v[2:3]
	v_add_co_u32_e32 v20, vcc, 0x60000, v24
	s_nop 1
	v_addc_co_u32_e32 v21, vcc, 0, v25, vcc
	v_add_co_u32_e32 v26, vcc, 0x1000, v24
	global_load_dwordx4 v[32:35], v[24:25], off
	s_nop 0
	global_load_dwordx4 v[20:23], v[20:21], off
	v_addc_co_u32_e32 v27, vcc, 0, v25, vcc
	s_waitcnt vmcnt(2)
	v_add_co_u32_e32 v28, vcc, 0x61000, v24
	s_nop 1
	v_addc_co_u32_e32 v29, vcc, 0, v25, vcc
	global_load_dwordx4 v[24:27], v[26:27], off
	s_nop 0
	global_load_dwordx4 v[28:31], v[28:29], off

; #define ATT_LOAD(kc) do { const bf16* p_ = kbase + (size_t)(kc) * 64 * NPROJ; rk0 = *(const v4u*)p_; rk1 = *(const v4u*)(p_ + (size_t)32 * NPROJ); \
;                           rv0 = *(const v4u*)(p_ + 2048); rv1 = *(const v4u*)(p_ + (size_t)32 * NPROJ + 2048); } while (0)
; #define ATT_WRITE(buf) do { ATT_KNORM(rk0, srow, buf); ATT_KNORM(rk1, srow + 32, buf); \
;             *(LAS v4u*)(lds + VB0 + (buf) * VBUF + srow * VS + sch * 16) = rv0; *(LAS v4u*)(lds + VB0 + (buf) * VBUF + (srow + 32) * VS + sch * 16) = rv1; } while (0)
; __device__ __forceinline__ void attn_phase(LAS unsigned char* lds, const bf16* qkv, const float* gq, const float* gk, const float* relb, bf16* ao, int tid, int lane, int w) {
;     ...
;         for (int t = 0; t < ntiles; ++t) {
;             const int kc = kc_lo + t, buf = t & 1;
;             if (t + 1 < ntiles) ATT_WRITE(buf ^ 1);
;             if (t + 2 < ntiles) ATT_LOAD(kc + 2);
.LBB0_339:
	s_add_i32 s8, s22, -2
	s_and_b32 s8, s8, 1
	s_add_i32 s9, s22, -1
	s_cmp_ge_i32 s9, s5
	s_cbranch_scc1 .LBB0_341
	s_cmp_lg_u32 s24, 0
	s_cbranch_scc1 .LBB0_341
	s_waitcnt vmcnt(3)
	v_and_b32_e32 v89, 0xffff0000, v35
	v_and_b32_e32 v87, 0xffff0000, v34
	v_lshlrev_b32_e32 v88, 16, v35
	v_lshlrev_b32_e32 v86, 16, v34
	v_mov_b32_e32 v90, v89
	v_mov_b32_e32 v91, v87
	v_mov_b32_e32 v84, v88
	v_mov_b32_e32 v85, v86
	v_pk_mul_f32 v[90:91], v[90:91], v[90:91]
	v_and_b32_e32 v93, 0xffff0000, v32
	v_pk_fma_f32 v[84:85], v[84:85], v[84:85], v[90:91]
	v_and_b32_e32 v91, 0xffff0000, v33
	v_lshlrev_b32_e32 v90, 16, v33
	v_lshlrev_b32_e32 v92, 16, v32
	v_mov_b32_e32 v96, v93
	v_mov_b32_e32 v97, v91
	v_mov_b32_e32 v94, v92
	v_mov_b32_e32 v95, v90
	v_pk_mul_f32 v[96:97], v[96:97], v[96:97]
	s_xor_b32 s9, s8, 1
	v_pk_fma_f32 v[94:95], v[94:95], v[94:95], v[96:97]
	s_mul_i32 s10, s9, 0x4400
	v_add_f32_e32 v94, v94, v95
	v_add_f32_e32 v85, v85, v94
	v_add_f32_e32 v84, v84, v85
	s_add_i32 s10, s10, 0
	s_lshl_b32 s9, s9, 10
	v_add_f32_dpp v84, v84, v84 quad_perm:[1,0,3,2] row_mask:0xf bank_mask:0xf bound_ctrl:1
	s_nop 1
	v_add_f32_dpp v84, v84, v84 quad_perm:[2,3,0,1] row_mask:0xf bank_mask:0xf bound_ctrl:1
	s_nop 1
	v_add_f32_dpp v84, v84, v84 row_half_mirror row_mask:0xf bank_mask:0xf bound_ctrl:1
	s_nop 1
	v_add_f32_dpp v84, v84, v84 row_mirror row_mask:0xf bank_mask:0xf bound_ctrl:1
	v_fmamk_f32 v84, v84, 0x3c000000, v207
	v_rsq_f32_e32 v94, v84
	s_nop 0
	v_pk_mul_f32 v[84:85], v[94:95], v[92:93] op_sel_hi:[0,1]
	v_pk_mul_f32 v[90:91], v[94:95], v[90:91] op_sel_hi:[0,1]
	v_pk_mul_f32 v[86:87], v[94:95], v[86:87] op_sel_hi:[0,1]
	v_pk_mul_f32 v[88:89], v[94:95], v[88:89] op_sel_hi:[0,1]
	v_cvt_pk_bf16_f32 v84, v84, v85
	v_cvt_pk_bf16_f32 v85, v90, v91
	v_cvt_pk_bf16_f32 v86, v86, v87
	v_cvt_pk_bf16_f32 v87, v88, v89
	v_add3_u32 v88, s10, v103, v102
	ds_write_b128 v88, v[84:87]
	s_waitcnt vmcnt(2)
	v_and_b32_e32 v89, 0xffff0000, v23
	v_and_b32_e32 v87, 0xffff0000, v22
	v_lshlrev_b32_e32 v88, 16, v23
	v_lshlrev_b32_e32 v86, 16, v22
	v_mov_b32_e32 v90, v89
	v_mov_b32_e32 v91, v87
	v_mov_b32_e32 v84, v88
	v_mov_b32_e32 v85, v86
	v_pk_mul_f32 v[90:91], v[90:91], v[90:91]
	v_and_b32_e32 v93, 0xffff0000, v20
	v_pk_fma_f32 v[84:85], v[84:85], v[84:85], v[90:91]
	v_and_b32_e32 v91, 0xffff0000, v21
	v_lshlrev_b32_e32 v90, 16, v21
	v_lshlrev_b32_e32 v92, 16, v20
	v_mov_b32_e32 v96, v93
	v_mov_b32_e32 v97, v91
	v_mov_b32_e32 v94, v92
	v_mov_b32_e32 v95, v90
	v_pk_mul_f32 v[96:97], v[96:97], v[96:97]
	s_nop 0
	v_pk_fma_f32 v[94:95], v[94:95], v[94:95], v[96:97]
	s_nop 0
	v_add_f32_e32 v94, v94, v95
	v_add_f32_e32 v85, v85, v94
	v_add_f32_e32 v84, v84, v85
	s_nop 1
	v_add_f32_dpp v84, v84, v84 quad_perm:[1,0,3,2] row_mask:0xf bank_mask:0xf bound_ctrl:1
	s_nop 1
	v_add_f32_dpp v84, v84, v84 quad_perm:[2,3,0,1] row_mask:0xf bank_mask:0xf bound_ctrl:1
	s_nop 1
	v_add_f32_dpp v84, v84, v84 row_half_mirror row_mask:0xf bank_mask:0xf bound_ctrl:1
	s_nop 1
	v_add_f32_dpp v84, v84, v84 row_mirror row_mask:0xf bank_mask:0xf bound_ctrl:1
	v_fmamk_f32 v84, v84, 0x3c000000, v207
	v_rsq_f32_e32 v94, v84
	s_nop 0
	v_pk_mul_f32 v[84:85], v[94:95], v[92:93] op_sel_hi:[0,1]
	v_pk_mul_f32 v[90:91], v[94:95], v[90:91] op_sel_hi:[0,1]
	v_pk_mul_f32 v[86:87], v[94:95], v[86:87] op_sel_hi:[0,1]
	v_pk_mul_f32 v[88:89], v[94:95], v[88:89] op_sel_hi:[0,1]
	v_cvt_pk_bf16_f32 v84, v84, v85
	v_cvt_pk_bf16_f32 v85, v90, v91
	v_cvt_pk_bf16_f32 v86, v86, v87
	v_cvt_pk_bf16_f32 v87, v88, v89
	v_add3_u32 v88, s10, v170, v102
	s_add_i32 s10, s10, s9
	ds_write_b128 v88, v[84:87]
	v_add3_u32 v84, s10, v171, v102
	s_waitcnt vmcnt(1)
	ds_write_b128 v84, v[24:27] offset:34816
	v_add3_u32 v84, s10, v173, v102
	s_waitcnt vmcnt(0)
	ds_write_b128 v84, v[28:31] offset:34816
.LBB0_341:
	s_add_i32 s9, s2, s22
	s_cmp_lt_i32 s22, s5
	s_cselect_b64 s[16:17], -1, 0
	s_cmp_ge_i32 s22, s5
	s_cbranch_scc1 .LBB0_343
	s_cmp_lg_u32 s24, 0
	s_cbranch_scc1 .LBB0_343
	s_add_i32 s10, s9, -8
	s_waitcnt vmcnt(1)
	v_mad_i64_i32 v[24:25], s[10:11], s10, v211, v[2:3]
	v_add_co_u32_e32 v20, vcc, 0x60000, v24
	s_nop 1
	v_addc_co_u32_e32 v21, vcc, 0, v25, vcc
	v_add_co_u32_e32 v26, vcc, 0x1000, v24
	global_load_dwordx4 v[32:35], v[24:25], off
	s_nop 0
	global_load_dwordx4 v[20:23], v[20:21], off
	v_addc_co_u32_e32 v27, vcc, 0, v25, vcc
	s_waitcnt vmcnt(2)
	v_add_co_u32_e32 v28, vcc, 0x61000, v24
	s_nop 1
	v_addc_co_u32_e32 v29, vcc, 0, v25, vcc
	global_load_dwordx4 v[24:27], v[26:27], off
	s_nop 0
	global_load_dwordx4 v[28:31], v[28:29], off
